# gdn output pass: hand-scheduled block body with factored decay (guarded per block); plus earlier gdn transition-pass rewrite and phase-12 rebalancing
# speedup vs baseline: 1.0091x; 1.0091x over previous
; template <int CTRL> __device__ __forceinline__ float dppf(float v) { return __builtin_bit_cast(float, __builtin_amdgcn_update_dpp(0, __builtin_bit_cast(int, v), CTRL, 0xF, 0xF, true)); }
; template <int MODE>
; __device__ __forceinline__ void gdn_job(const Params& P, float* lw, int head, int rb, int seg) {
;     ...
;         for (int s = 0; s < TBK; ++s) {
;             f32x2 k[8], q[8]; f32x4 v = {0.f, 0.f, 0.f, 0.f};
; #pragma unroll
;             for (int q4 = 0; q4 < 4; ++q4) { const f32x4 x = *(const f32x4*)(sk + s * 128 + jg * 16 + q4 * 4); k[2 * q4] = (f32x2){x.x, x.y}; k[2 * q4 + 1] = (f32x2){x.z, x.w}; }
;             if (MODE == 2) {
; #pragma unroll
;                 for (int q4 = 0; q4 < 4; ++q4) { const f32x4 x = *(const f32x4*)(sq + s * 128 + jg * 16 + q4 * 4); q[2 * q4] = (f32x2){x.x, x.y}; q[2 * q4 + 1] = (f32x2){x.z, x.w}; }
;             }
;             if (MODE != 0) v = *(const f32x4*)(sv + s * 32 + ig * 4);
;             const float al = sal[s], be = sbe[s];
;             float ok = 0.f;
;             float sa[4];
; #pragma unroll
;             for (int ri = 0; ri < 4; ++ri) {
;                 f32x2 a2 = S[ri][0] * k[0], a3 = S[ri][1] * k[1];
; #pragma unroll
;                 for (int jj = 2; jj < 8; jj += 2) { a2 += S[ri][jj] * k[jj]; a3 += S[ri][jj + 1] * k[jj + 1]; }
;                 a2 += a3; sa[ri] = a2.x + a2.y;
;             }
; #pragma unroll
;             for (int ri = 0; ri < 4; ++ri) sa[ri] += dppf<0xB1>(sa[ri]);
; #pragma unroll
;             for (int ri = 0; ri < 4; ++ri) sa[ri] += dppf<0x4E>(sa[ri]);
; #pragma unroll
;             for (int ri = 0; ri < 4; ++ri) sa[ri] += dppf<0x141>(sa[ri]);
; #pragma unroll
;             for (int ri = 0; ri < 4; ++ri) {
;                 const float c = (MODE != 0) ? be * (v[ri] - al * sa[ri]) : -be * al * sa[ri];
; #pragma unroll
;                 for (int jj = 0; jj < 8; ++jj) S[ri][jj] = S[ri][jj] * al + k[jj] * c;
;             }
.LBB0_667:
	s_mov_b64 s[66:67], 0
	v_mov_b32_e32 v84, v117
	v_mov_b32_e32 v91, v116
	s_mov_b32 s73, s70
	v_add_u32_e32 v220, s70, v133
	ds_read_b128 v[224:227], v220
	ds_read_b128 v[228:231], v220 offset:16
	s_waitcnt lgkmcnt(0)
	v_mul_f32_e32 v224, v224, v225
	v_mul_f32_e32 v226, v226, v227
	v_mul_f32_e32 v228, v228, v229
	v_mul_f32_e32 v230, v230, v231
	v_mul_f32_e32 v224, v224, v226
	v_mul_f32_e32 v228, v228, v230
	v_mul_f32_e32 v224, v224, v228
	s_nop 0
	v_readfirstlane_b32 s100, v224
	s_cmp_lt_u32 s100, 0x0d800000
	s_cbranch_scc1 .LBB0_669
	v_mov_b32_e32 v236, 1.0
.Lc2_fast:
	v_add_u32_e32 v95, v84, v133
	v_add_u32_e32 v103, v91, v133
	v_add_u32_e32 v126, s73, v133
	ds_read_b128 v[138:141], v95 offset:0
	ds_read_b128 v[142:145], v95 offset:16
	ds_read_b128 v[146:149], v95 offset:32
	ds_read_b128 v[150:153], v95 offset:48
	ds_read2_b32 v[108:109], v126 offset1:8
	ds_read2_b32 v[232:233], v126 offset0:1 offset1:9
	ds_read_b128 v[178:181], v103
	ds_read_b128 v[154:157], v95 offset:4096
	ds_read_b128 v[166:169], v95 offset:4112
	ds_read_b128 v[170:173], v95 offset:4128
	ds_read_b128 v[174:177], v95 offset:4144
	v_lshl_add_u64 v[224:225], v[106:107], 0, s[66:67]
	s_waitcnt lgkmcnt(4)
	v_mul_f32_e32 v236, v236, v108
	v_rcp_f32_e32 v234, v236
	v_pk_mul_f32 v[128:129], v[30:31], v[138:139]
	v_pk_mul_f32 v[134:135], v[46:47], v[138:139]
	v_pk_mul_f32 v[220:221], v[62:63], v[138:139]
	v_pk_mul_f32 v[222:223], v[78:79], v[138:139]
	v_pk_fma_f32 v[128:129], v[32:33], v[140:141], v[128:129]
	v_pk_fma_f32 v[134:135], v[48:49], v[140:141], v[134:135]
	v_pk_fma_f32 v[220:221], v[64:65], v[140:141], v[220:221]
	v_pk_fma_f32 v[222:223], v[80:81], v[140:141], v[222:223]
	v_pk_fma_f32 v[128:129], v[26:27], v[142:143], v[128:129]
	v_pk_fma_f32 v[134:135], v[42:43], v[142:143], v[134:135]
	v_pk_fma_f32 v[220:221], v[58:59], v[142:143], v[220:221]
	v_pk_fma_f32 v[222:223], v[74:75], v[142:143], v[222:223]
	v_pk_fma_f32 v[128:129], v[28:29], v[144:145], v[128:129]
	v_pk_fma_f32 v[134:135], v[44:45], v[144:145], v[134:135]
	v_pk_fma_f32 v[220:221], v[60:61], v[144:145], v[220:221]
	v_pk_fma_f32 v[222:223], v[76:77], v[144:145], v[222:223]
	v_pk_fma_f32 v[128:129], v[22:23], v[146:147], v[128:129]
	v_pk_fma_f32 v[134:135], v[38:39], v[146:147], v[134:135]
	v_pk_fma_f32 v[220:221], v[54:55], v[146:147], v[220:221]
	v_pk_fma_f32 v[222:223], v[70:71], v[146:147], v[222:223]
	v_pk_fma_f32 v[128:129], v[24:25], v[148:149], v[128:129]
	v_pk_fma_f32 v[134:135], v[40:41], v[148:149], v[134:135]
	v_pk_fma_f32 v[220:221], v[56:57], v[148:149], v[220:221]
	v_pk_fma_f32 v[222:223], v[72:73], v[148:149], v[222:223]
	v_pk_fma_f32 v[128:129], v[18:19], v[150:151], v[128:129]
	v_pk_fma_f32 v[134:135], v[34:35], v[150:151], v[134:135]
	v_pk_fma_f32 v[220:221], v[50:51], v[150:151], v[220:221]
	v_pk_fma_f32 v[222:223], v[66:67], v[150:151], v[222:223]
	v_pk_fma_f32 v[128:129], v[20:21], v[152:153], v[128:129]
	v_pk_fma_f32 v[134:135], v[36:37], v[152:153], v[134:135]
	v_pk_fma_f32 v[220:221], v[52:53], v[152:153], v[220:221]
	v_pk_fma_f32 v[222:223], v[68:69], v[152:153], v[222:223]
	v_add_f32_e32 v128, v128, v129
	v_add_f32_e32 v134, v134, v135
	v_add_f32_e32 v220, v220, v221
	v_add_f32_e32 v222, v222, v223
	v_add_f32_dpp v128, v128, v128 quad_perm:[1,0,3,2] row_mask:0xf bank_mask:0xf bound_ctrl:1
	v_add_f32_dpp v134, v134, v134 quad_perm:[1,0,3,2] row_mask:0xf bank_mask:0xf bound_ctrl:1
	v_add_f32_dpp v220, v220, v220 quad_perm:[1,0,3,2] row_mask:0xf bank_mask:0xf bound_ctrl:1
	v_add_f32_dpp v222, v222, v222 quad_perm:[1,0,3,2] row_mask:0xf bank_mask:0xf bound_ctrl:1
	v_add_f32_dpp v128, v128, v128 quad_perm:[2,3,0,1] row_mask:0xf bank_mask:0xf bound_ctrl:1
	v_add_f32_dpp v134, v134, v134 quad_perm:[2,3,0,1] row_mask:0xf bank_mask:0xf bound_ctrl:1
	v_add_f32_dpp v220, v220, v220 quad_perm:[2,3,0,1] row_mask:0xf bank_mask:0xf bound_ctrl:1
	v_add_f32_dpp v222, v222, v222 quad_perm:[2,3,0,1] row_mask:0xf bank_mask:0xf bound_ctrl:1
	v_add_f32_dpp v128, v128, v128 row_half_mirror row_mask:0xf bank_mask:0xf bound_ctrl:1
	v_add_f32_dpp v134, v134, v134 row_half_mirror row_mask:0xf bank_mask:0xf bound_ctrl:1
	v_add_f32_dpp v220, v220, v220 row_half_mirror row_mask:0xf bank_mask:0xf bound_ctrl:1
	v_add_f32_dpp v222, v222, v222 row_half_mirror row_mask:0xf bank_mask:0xf bound_ctrl:1
	v_mul_f32_e32 v235, v109, v234
	v_mul_f32_e64 v128, v128, -v109
	v_mul_f32_e64 v134, v134, -v109
	v_mul_f32_e64 v220, v220, -v109
	v_mul_f32_e64 v222, v222, -v109
	v_fmac_f32_e32 v128, v178, v235
	v_fmac_f32_e32 v134, v179, v235
	v_fmac_f32_e32 v220, v180, v235
	v_fmac_f32_e32 v222, v181, v235
	v_pk_fma_f32 v[30:31], v[138:139], v[128:129], v[30:31] op_sel_hi:[1,0,1]
	v_pk_fma_f32 v[32:33], v[140:141], v[128:129], v[32:33] op_sel_hi:[1,0,1]
	v_pk_fma_f32 v[26:27], v[142:143], v[128:129], v[26:27] op_sel_hi:[1,0,1]
	v_pk_fma_f32 v[28:29], v[144:145], v[128:129], v[28:29] op_sel_hi:[1,0,1]
	v_pk_fma_f32 v[22:23], v[146:147], v[128:129], v[22:23] op_sel_hi:[1,0,1]
	v_pk_fma_f32 v[24:25], v[148:149], v[128:129], v[24:25] op_sel_hi:[1,0,1]
	v_pk_fma_f32 v[18:19], v[150:151], v[128:129], v[18:19] op_sel_hi:[1,0,1]
	v_pk_fma_f32 v[20:21], v[152:153], v[128:129], v[20:21] op_sel_hi:[1,0,1]
	v_pk_fma_f32 v[46:47], v[138:139], v[134:135], v[46:47] op_sel_hi:[1,0,1]
	v_pk_fma_f32 v[48:49], v[140:141], v[134:135], v[48:49] op_sel_hi:[1,0,1]
	v_pk_fma_f32 v[42:43], v[142:143], v[134:135], v[42:43] op_sel_hi:[1,0,1]
	v_pk_fma_f32 v[44:45], v[144:145], v[134:135], v[44:45] op_sel_hi:[1,0,1]
	v_pk_fma_f32 v[38:39], v[146:147], v[134:135], v[38:39] op_sel_hi:[1,0,1]
	v_pk_fma_f32 v[40:41], v[148:149], v[134:135], v[40:41] op_sel_hi:[1,0,1]
; __device__ __forceinline__ bf16_t f2bf(float f) { return (bf16_t)(cvt_pk_bf16(f, 0.f) & 0xffffu); }
; template <int CTRL> __device__ __forceinline__ float dppf(float v) { return __builtin_bit_cast(float, __builtin_amdgcn_update_dpp(0, __builtin_bit_cast(int, v), CTRL, 0xF, 0xF, true)); }
; template <int MODE>
; __device__ __forceinline__ void gdn_job(const Params& P, float* lw, int head, int rb, int seg) {
;     ...
;             for (int ri = 0; ri < 4; ++ri) sa[ri] += dppf<0x141>(sa[ri]);
; #pragma unroll
;             for (int ri = 0; ri < 4; ++ri) {
;                 const float c = (MODE != 0) ? be * (v[ri] - al * sa[ri]) : -be * al * sa[ri];
; #pragma unroll
;                 for (int jj = 0; jj < 8; ++jj) S[ri][jj] = S[ri][jj] * al + k[jj] * c;
;             }
;             if (MODE == 2) {
;                 float os[4];
; #pragma unroll
;                 for (int ri = 0; ri < 4; ++ri) {
;                     f32x2 o2 = S[ri][0] * q[0], o3 = S[ri][1] * q[1];
; #pragma unroll
;                     for (int jj = 2; jj < 8; jj += 2) { o2 += S[ri][jj] * q[jj]; o3 += S[ri][jj + 1] * q[jj + 1]; }
;                     o2 += o3; os[ri] = o2.x + o2.y;
;                 }
; #pragma unroll
;                 for (int ri = 0; ri < 4; ++ri) os[ri] += dppf<0xB1>(os[ri]);
; #pragma unroll
;                 for (int ri = 0; ri < 4; ++ri) os[ri] += dppf<0x4E>(os[ri]);
; #pragma unroll
;                 for (int ri = 0; ri < 4; ++ri) os[ri] += dppf<0x141>(os[ri]);
; #pragma unroll
;                 for (int ri = 0; ri < 4; ++ri) ok = (jg == ri) ? os[ri] : ok;
;             }
;             if (MODE == 2) { if (jg < 4) proj[(size_t)(tbase + blk * TBK + s) * PLD + PC_GQKV + head * 128 + row0 + jg] = f2bf(ok); }
	v_pk_fma_f32 v[34:35], v[150:151], v[134:135], v[34:35] op_sel_hi:[1,0,1]
	v_pk_fma_f32 v[36:37], v[152:153], v[134:135], v[36:37] op_sel_hi:[1,0,1]
	v_pk_fma_f32 v[62:63], v[138:139], v[220:221], v[62:63] op_sel_hi:[1,0,1]
	v_pk_fma_f32 v[64:65], v[140:141], v[220:221], v[64:65] op_sel_hi:[1,0,1]
	v_pk_fma_f32 v[58:59], v[142:143], v[220:221], v[58:59] op_sel_hi:[1,0,1]
	v_pk_fma_f32 v[60:61], v[144:145], v[220:221], v[60:61] op_sel_hi:[1,0,1]
	v_pk_fma_f32 v[54:55], v[146:147], v[220:221], v[54:55] op_sel_hi:[1,0,1]
	v_pk_fma_f32 v[56:57], v[148:149], v[220:221], v[56:57] op_sel_hi:[1,0,1]
	v_pk_fma_f32 v[50:51], v[150:151], v[220:221], v[50:51] op_sel_hi:[1,0,1]
	v_pk_fma_f32 v[52:53], v[152:153], v[220:221], v[52:53] op_sel_hi:[1,0,1]
	v_pk_fma_f32 v[78:79], v[138:139], v[222:223], v[78:79] op_sel_hi:[1,0,1]
	v_pk_fma_f32 v[80:81], v[140:141], v[222:223], v[80:81] op_sel_hi:[1,0,1]
	v_pk_fma_f32 v[74:75], v[142:143], v[222:223], v[74:75] op_sel_hi:[1,0,1]
	v_pk_fma_f32 v[76:77], v[144:145], v[222:223], v[76:77] op_sel_hi:[1,0,1]
	v_pk_fma_f32 v[70:71], v[146:147], v[222:223], v[70:71] op_sel_hi:[1,0,1]
	v_pk_fma_f32 v[72:73], v[148:149], v[222:223], v[72:73] op_sel_hi:[1,0,1]
	v_pk_fma_f32 v[66:67], v[150:151], v[222:223], v[66:67] op_sel_hi:[1,0,1]
	v_pk_fma_f32 v[68:69], v[152:153], v[222:223], v[68:69] op_sel_hi:[1,0,1]
	ds_read_b128 v[138:141], v95 offset:512
	ds_read_b128 v[142:145], v95 offset:528
	ds_read_b128 v[146:149], v95 offset:544
	ds_read_b128 v[150:153], v95 offset:560
	ds_read_b128 v[178:181], v103 offset:128
	s_waitcnt lgkmcnt(5)
	v_pk_mul_f32 v[128:129], v[30:31], v[154:155]
	v_pk_mul_f32 v[134:135], v[46:47], v[154:155]
	v_pk_mul_f32 v[220:221], v[62:63], v[154:155]
	v_pk_mul_f32 v[222:223], v[78:79], v[154:155]
	v_pk_fma_f32 v[128:129], v[32:33], v[156:157], v[128:129]
	v_pk_fma_f32 v[134:135], v[48:49], v[156:157], v[134:135]
	v_pk_fma_f32 v[220:221], v[64:65], v[156:157], v[220:221]
	v_pk_fma_f32 v[222:223], v[80:81], v[156:157], v[222:223]
	v_pk_fma_f32 v[128:129], v[26:27], v[166:167], v[128:129]
	v_pk_fma_f32 v[134:135], v[42:43], v[166:167], v[134:135]
	v_pk_fma_f32 v[220:221], v[58:59], v[166:167], v[220:221]
	v_pk_fma_f32 v[222:223], v[74:75], v[166:167], v[222:223]
	v_pk_fma_f32 v[128:129], v[28:29], v[168:169], v[128:129]
	v_pk_fma_f32 v[134:135], v[44:45], v[168:169], v[134:135]
	v_pk_fma_f32 v[220:221], v[60:61], v[168:169], v[220:221]
	v_pk_fma_f32 v[222:223], v[76:77], v[168:169], v[222:223]
	v_pk_fma_f32 v[128:129], v[22:23], v[170:171], v[128:129]
	v_pk_fma_f32 v[134:135], v[38:39], v[170:171], v[134:135]
	v_pk_fma_f32 v[220:221], v[54:55], v[170:171], v[220:221]
	v_pk_fma_f32 v[222:223], v[70:71], v[170:171], v[222:223]
	v_pk_fma_f32 v[128:129], v[24:25], v[172:173], v[128:129]
	v_pk_fma_f32 v[134:135], v[40:41], v[172:173], v[134:135]
	v_pk_fma_f32 v[220:221], v[56:57], v[172:173], v[220:221]
	v_pk_fma_f32 v[222:223], v[72:73], v[172:173], v[222:223]
	v_pk_fma_f32 v[128:129], v[18:19], v[174:175], v[128:129]
	v_pk_fma_f32 v[134:135], v[34:35], v[174:175], v[134:135]
	v_pk_fma_f32 v[220:221], v[50:51], v[174:175], v[220:221]
	v_pk_fma_f32 v[222:223], v[66:67], v[174:175], v[222:223]
	v_pk_fma_f32 v[128:129], v[20:21], v[176:177], v[128:129]
	v_pk_fma_f32 v[134:135], v[36:37], v[176:177], v[134:135]
	v_pk_fma_f32 v[220:221], v[52:53], v[176:177], v[220:221]
	v_pk_fma_f32 v[222:223], v[68:69], v[176:177], v[222:223]
	v_add_f32_e32 v128, v128, v129
	v_add_f32_e32 v134, v134, v135
	v_add_f32_e32 v220, v220, v221
	v_add_f32_e32 v222, v222, v223
	v_add_f32_dpp v128, v128, v128 quad_perm:[1,0,3,2] row_mask:0xf bank_mask:0xf bound_ctrl:1
	v_add_f32_dpp v134, v134, v134 quad_perm:[1,0,3,2] row_mask:0xf bank_mask:0xf bound_ctrl:1
	v_add_f32_dpp v220, v220, v220 quad_perm:[1,0,3,2] row_mask:0xf bank_mask:0xf bound_ctrl:1
	v_add_f32_dpp v222, v222, v222 quad_perm:[1,0,3,2] row_mask:0xf bank_mask:0xf bound_ctrl:1
	v_add_f32_dpp v128, v128, v128 quad_perm:[2,3,0,1] row_mask:0xf bank_mask:0xf bound_ctrl:1
	v_add_f32_dpp v134, v134, v134 quad_perm:[2,3,0,1] row_mask:0xf bank_mask:0xf bound_ctrl:1
	v_add_f32_dpp v220, v220, v220 quad_perm:[2,3,0,1] row_mask:0xf bank_mask:0xf bound_ctrl:1
	v_add_f32_dpp v222, v222, v222 quad_perm:[2,3,0,1] row_mask:0xf bank_mask:0xf bound_ctrl:1
	v_add_f32_dpp v128, v128, v128 row_half_mirror row_mask:0xf bank_mask:0xf bound_ctrl:1
	v_add_f32_dpp v134, v134, v134 row_half_mirror row_mask:0xf bank_mask:0xf bound_ctrl:1
	v_add_f32_dpp v220, v220, v220 row_half_mirror row_mask:0xf bank_mask:0xf bound_ctrl:1
	v_add_f32_dpp v222, v222, v222 row_half_mirror row_mask:0xf bank_mask:0xf bound_ctrl:1
	ds_read_b128 v[154:157], v95 offset:4608
	ds_read_b128 v[166:169], v95 offset:4624
	ds_read_b128 v[170:173], v95 offset:4640
	ds_read_b128 v[174:177], v95 offset:4656
	v_mul_f32_e32 v128, v128, v236
	v_mul_f32_e32 v134, v134, v236
	v_mul_f32_e32 v220, v220, v236
	v_mul_f32_e32 v222, v222, v236
	s_and_saveexec_b64 s[68:69], s[8:9]
	v_cndmask_b32_e64 v226, 0, v128, s[10:11]
	v_cndmask_b32_e64 v226, v226, v134, s[12:13]
	v_cndmask_b32_e64 v226, v226, v220, s[14:15]
	v_cndmask_b32_e64 v226, v226, v222, s[16:17]
	v_add_co_u32_e32 v228, vcc, 0xdc01000, v224
	v_cvt_pk_bf16_f32 v226, v226, s0
	s_nop 0
	v_addc_co_u32_e32 v229, vcc, 0, v225, vcc
	global_store_short v[228:229], v226, off offset:2048
	s_or_b64 exec, exec, s[68:69]
	s_waitcnt lgkmcnt(4)
; template <int CTRL> __device__ __forceinline__ float dppf(float v) { return __builtin_bit_cast(float, __builtin_amdgcn_update_dpp(0, __builtin_bit_cast(int, v), CTRL, 0xF, 0xF, true)); }
; template <int MODE>
; __device__ __forceinline__ void gdn_job(const Params& P, float* lw, int head, int rb, int seg) {
;     ...
;         for (int s = 0; s < TBK; ++s) {
;             f32x2 k[8], q[8]; f32x4 v = {0.f, 0.f, 0.f, 0.f};
; #pragma unroll
;             for (int q4 = 0; q4 < 4; ++q4) { const f32x4 x = *(const f32x4*)(sk + s * 128 + jg * 16 + q4 * 4); k[2 * q4] = (f32x2){x.x, x.y}; k[2 * q4 + 1] = (f32x2){x.z, x.w}; }
;             if (MODE == 2) {
; #pragma unroll
;                 for (int q4 = 0; q4 < 4; ++q4) { const f32x4 x = *(const f32x4*)(sq + s * 128 + jg * 16 + q4 * 4); q[2 * q4] = (f32x2){x.x, x.y}; q[2 * q4 + 1] = (f32x2){x.z, x.w}; }
;             }
;             if (MODE != 0) v = *(const f32x4*)(sv + s * 32 + ig * 4);
;             const float al = sal[s], be = sbe[s];
;             float ok = 0.f;
;             float sa[4];
; #pragma unroll
;             for (int ri = 0; ri < 4; ++ri) {
;                 f32x2 a2 = S[ri][0] * k[0], a3 = S[ri][1] * k[1];
; #pragma unroll
;                 for (int jj = 2; jj < 8; jj += 2) { a2 += S[ri][jj] * k[jj]; a3 += S[ri][jj + 1] * k[jj + 1]; }
;                 a2 += a3; sa[ri] = a2.x + a2.y;
;             }
; #pragma unroll
;             for (int ri = 0; ri < 4; ++ri) sa[ri] += dppf<0xB1>(sa[ri]);
; #pragma unroll
;             for (int ri = 0; ri < 4; ++ri) sa[ri] += dppf<0x4E>(sa[ri]);
; #pragma unroll
;             for (int ri = 0; ri < 4; ++ri) sa[ri] += dppf<0x141>(sa[ri]);
; #pragma unroll
;             for (int ri = 0; ri < 4; ++ri) {
;                 const float c = (MODE != 0) ? be * (v[ri] - al * sa[ri]) : -be * al * sa[ri];
; #pragma unroll
;                 for (int jj = 0; jj < 8; ++jj) S[ri][jj] = S[ri][jj] * al + k[jj] * c;
;             }
	v_mul_f32_e32 v236, v236, v232
	v_rcp_f32_e32 v234, v236
	v_pk_mul_f32 v[128:129], v[30:31], v[138:139]
	v_pk_mul_f32 v[134:135], v[46:47], v[138:139]
	v_pk_mul_f32 v[220:221], v[62:63], v[138:139]
	v_pk_mul_f32 v[222:223], v[78:79], v[138:139]
	v_pk_fma_f32 v[128:129], v[32:33], v[140:141], v[128:129]
	v_pk_fma_f32 v[134:135], v[48:49], v[140:141], v[134:135]
	v_pk_fma_f32 v[220:221], v[64:65], v[140:141], v[220:221]
	v_pk_fma_f32 v[222:223], v[80:81], v[140:141], v[222:223]
	v_pk_fma_f32 v[128:129], v[26:27], v[142:143], v[128:129]
	v_pk_fma_f32 v[134:135], v[42:43], v[142:143], v[134:135]
	v_pk_fma_f32 v[220:221], v[58:59], v[142:143], v[220:221]
	v_pk_fma_f32 v[222:223], v[74:75], v[142:143], v[222:223]
	v_pk_fma_f32 v[128:129], v[28:29], v[144:145], v[128:129]
	v_pk_fma_f32 v[134:135], v[44:45], v[144:145], v[134:135]
	v_pk_fma_f32 v[220:221], v[60:61], v[144:145], v[220:221]
	v_pk_fma_f32 v[222:223], v[76:77], v[144:145], v[222:223]
	v_pk_fma_f32 v[128:129], v[22:23], v[146:147], v[128:129]
	v_pk_fma_f32 v[134:135], v[38:39], v[146:147], v[134:135]
	v_pk_fma_f32 v[220:221], v[54:55], v[146:147], v[220:221]
	v_pk_fma_f32 v[222:223], v[70:71], v[146:147], v[222:223]
	v_pk_fma_f32 v[128:129], v[24:25], v[148:149], v[128:129]
	v_pk_fma_f32 v[134:135], v[40:41], v[148:149], v[134:135]
	v_pk_fma_f32 v[220:221], v[56:57], v[148:149], v[220:221]
	v_pk_fma_f32 v[222:223], v[72:73], v[148:149], v[222:223]
	v_pk_fma_f32 v[128:129], v[18:19], v[150:151], v[128:129]
	v_pk_fma_f32 v[134:135], v[34:35], v[150:151], v[134:135]
	v_pk_fma_f32 v[220:221], v[50:51], v[150:151], v[220:221]
	v_pk_fma_f32 v[222:223], v[66:67], v[150:151], v[222:223]
	v_pk_fma_f32 v[128:129], v[20:21], v[152:153], v[128:129]
	v_pk_fma_f32 v[134:135], v[36:37], v[152:153], v[134:135]
	v_pk_fma_f32 v[220:221], v[52:53], v[152:153], v[220:221]
	v_pk_fma_f32 v[222:223], v[68:69], v[152:153], v[222:223]
	v_add_f32_e32 v128, v128, v129
	v_add_f32_e32 v134, v134, v135
	v_add_f32_e32 v220, v220, v221
	v_add_f32_e32 v222, v222, v223
	v_add_f32_dpp v128, v128, v128 quad_perm:[1,0,3,2] row_mask:0xf bank_mask:0xf bound_ctrl:1
	v_add_f32_dpp v134, v134, v134 quad_perm:[1,0,3,2] row_mask:0xf bank_mask:0xf bound_ctrl:1
	v_add_f32_dpp v220, v220, v220 quad_perm:[1,0,3,2] row_mask:0xf bank_mask:0xf bound_ctrl:1
	v_add_f32_dpp v222, v222, v222 quad_perm:[1,0,3,2] row_mask:0xf bank_mask:0xf bound_ctrl:1
	v_add_f32_dpp v128, v128, v128 quad_perm:[2,3,0,1] row_mask:0xf bank_mask:0xf bound_ctrl:1
	v_add_f32_dpp v134, v134, v134 quad_perm:[2,3,0,1] row_mask:0xf bank_mask:0xf bound_ctrl:1
	v_add_f32_dpp v220, v220, v220 quad_perm:[2,3,0,1] row_mask:0xf bank_mask:0xf bound_ctrl:1
	v_add_f32_dpp v222, v222, v222 quad_perm:[2,3,0,1] row_mask:0xf bank_mask:0xf bound_ctrl:1
	v_add_f32_dpp v128, v128, v128 row_half_mirror row_mask:0xf bank_mask:0xf bound_ctrl:1
	v_add_f32_dpp v134, v134, v134 row_half_mirror row_mask:0xf bank_mask:0xf bound_ctrl:1
	v_add_f32_dpp v220, v220, v220 row_half_mirror row_mask:0xf bank_mask:0xf bound_ctrl:1
	v_add_f32_dpp v222, v222, v222 row_half_mirror row_mask:0xf bank_mask:0xf bound_ctrl:1
	v_mul_f32_e32 v235, v233, v234
	v_mul_f32_e64 v128, v128, -v233
	v_mul_f32_e64 v134, v134, -v233
	v_mul_f32_e64 v220, v220, -v233
	v_mul_f32_e64 v222, v222, -v233
	v_fmac_f32_e32 v128, v178, v235
	v_fmac_f32_e32 v134, v179, v235
	v_fmac_f32_e32 v220, v180, v235
	v_fmac_f32_e32 v222, v181, v235
	v_pk_fma_f32 v[30:31], v[138:139], v[128:129], v[30:31] op_sel_hi:[1,0,1]
	v_pk_fma_f32 v[32:33], v[140:141], v[128:129], v[32:33] op_sel_hi:[1,0,1]
	v_pk_fma_f32 v[26:27], v[142:143], v[128:129], v[26:27] op_sel_hi:[1,0,1]
	v_pk_fma_f32 v[28:29], v[144:145], v[128:129], v[28:29] op_sel_hi:[1,0,1]
	v_pk_fma_f32 v[22:23], v[146:147], v[128:129], v[22:23] op_sel_hi:[1,0,1]
	v_pk_fma_f32 v[24:25], v[148:149], v[128:129], v[24:25] op_sel_hi:[1,0,1]
	v_pk_fma_f32 v[18:19], v[150:151], v[128:129], v[18:19] op_sel_hi:[1,0,1]
	v_pk_fma_f32 v[20:21], v[152:153], v[128:129], v[20:21] op_sel_hi:[1,0,1]
	v_pk_fma_f32 v[46:47], v[138:139], v[134:135], v[46:47] op_sel_hi:[1,0,1]
	v_pk_fma_f32 v[48:49], v[140:141], v[134:135], v[48:49] op_sel_hi:[1,0,1]
	v_pk_fma_f32 v[42:43], v[142:143], v[134:135], v[42:43] op_sel_hi:[1,0,1]
	v_pk_fma_f32 v[44:45], v[144:145], v[134:135], v[44:45] op_sel_hi:[1,0,1]
	v_pk_fma_f32 v[38:39], v[146:147], v[134:135], v[38:39] op_sel_hi:[1,0,1]
	v_pk_fma_f32 v[40:41], v[148:149], v[134:135], v[40:41] op_sel_hi:[1,0,1]
	v_pk_fma_f32 v[34:35], v[150:151], v[134:135], v[34:35] op_sel_hi:[1,0,1]
	v_pk_fma_f32 v[36:37], v[152:153], v[134:135], v[36:37] op_sel_hi:[1,0,1]
	v_pk_fma_f32 v[62:63], v[138:139], v[220:221], v[62:63] op_sel_hi:[1,0,1]
	v_pk_fma_f32 v[64:65], v[140:141], v[220:221], v[64:65] op_sel_hi:[1,0,1]
	v_pk_fma_f32 v[58:59], v[142:143], v[220:221], v[58:59] op_sel_hi:[1,0,1]
	v_pk_fma_f32 v[60:61], v[144:145], v[220:221], v[60:61] op_sel_hi:[1,0,1]
	v_pk_fma_f32 v[54:55], v[146:147], v[220:221], v[54:55] op_sel_hi:[1,0,1]
	v_pk_fma_f32 v[56:57], v[148:149], v[220:221], v[56:57] op_sel_hi:[1,0,1]
	v_pk_fma_f32 v[50:51], v[150:151], v[220:221], v[50:51] op_sel_hi:[1,0,1]
	v_pk_fma_f32 v[52:53], v[152:153], v[220:221], v[52:53] op_sel_hi:[1,0,1]
	v_pk_fma_f32 v[78:79], v[138:139], v[222:223], v[78:79] op_sel_hi:[1,0,1]
	v_pk_fma_f32 v[80:81], v[140:141], v[222:223], v[80:81] op_sel_hi:[1,0,1]
	v_pk_fma_f32 v[74:75], v[142:143], v[222:223], v[74:75] op_sel_hi:[1,0,1]
	v_pk_fma_f32 v[76:77], v[144:145], v[222:223], v[76:77] op_sel_hi:[1,0,1]
	v_pk_fma_f32 v[70:71], v[146:147], v[222:223], v[70:71] op_sel_hi:[1,0,1]
	v_pk_fma_f32 v[72:73], v[148:149], v[222:223], v[72:73] op_sel_hi:[1,0,1]
	v_pk_fma_f32 v[66:67], v[150:151], v[222:223], v[66:67] op_sel_hi:[1,0,1]
	v_pk_fma_f32 v[68:69], v[152:153], v[222:223], v[68:69] op_sel_hi:[1,0,1]
	s_waitcnt lgkmcnt(0)
; __device__ __forceinline__ bf16_t f2bf(float f) { return (bf16_t)(cvt_pk_bf16(f, 0.f) & 0xffffu); }
; template <int CTRL> __device__ __forceinline__ float dppf(float v) { return __builtin_bit_cast(float, __builtin_amdgcn_update_dpp(0, __builtin_bit_cast(int, v), CTRL, 0xF, 0xF, true)); }
; template <int MODE>
; __device__ __forceinline__ void gdn_job(const Params& P, float* lw, int head, int rb, int seg) {
;     ...
;             if (MODE == 2) {
;                 float os[4];
; #pragma unroll
;                 for (int ri = 0; ri < 4; ++ri) {
;                     f32x2 o2 = S[ri][0] * q[0], o3 = S[ri][1] * q[1];
; #pragma unroll
;                     for (int jj = 2; jj < 8; jj += 2) { o2 += S[ri][jj] * q[jj]; o3 += S[ri][jj + 1] * q[jj + 1]; }
;                     o2 += o3; os[ri] = o2.x + o2.y;
;                 }
; #pragma unroll
;                 for (int ri = 0; ri < 4; ++ri) os[ri] += dppf<0xB1>(os[ri]);
; #pragma unroll
;                 for (int ri = 0; ri < 4; ++ri) os[ri] += dppf<0x4E>(os[ri]);
; #pragma unroll
;                 for (int ri = 0; ri < 4; ++ri) os[ri] += dppf<0x141>(os[ri]);
; #pragma unroll
;                 for (int ri = 0; ri < 4; ++ri) ok = (jg == ri) ? os[ri] : ok;
;             }
;             if (MODE == 2) { if (jg < 4) proj[(size_t)(tbase + blk * TBK + s) * PLD + PC_GQKV + head * 128 + row0 + jg] = f2bf(ok); }
;         }
	v_pk_mul_f32 v[128:129], v[30:31], v[154:155]
	v_pk_mul_f32 v[134:135], v[46:47], v[154:155]
	v_pk_mul_f32 v[220:221], v[62:63], v[154:155]
	v_pk_mul_f32 v[222:223], v[78:79], v[154:155]
	v_pk_fma_f32 v[128:129], v[32:33], v[156:157], v[128:129]
	v_pk_fma_f32 v[134:135], v[48:49], v[156:157], v[134:135]
	v_pk_fma_f32 v[220:221], v[64:65], v[156:157], v[220:221]
	v_pk_fma_f32 v[222:223], v[80:81], v[156:157], v[222:223]
	v_pk_fma_f32 v[128:129], v[26:27], v[166:167], v[128:129]
	v_pk_fma_f32 v[134:135], v[42:43], v[166:167], v[134:135]
	v_pk_fma_f32 v[220:221], v[58:59], v[166:167], v[220:221]
	v_pk_fma_f32 v[222:223], v[74:75], v[166:167], v[222:223]
	v_pk_fma_f32 v[128:129], v[28:29], v[168:169], v[128:129]
	v_pk_fma_f32 v[134:135], v[44:45], v[168:169], v[134:135]
	v_pk_fma_f32 v[220:221], v[60:61], v[168:169], v[220:221]
	v_pk_fma_f32 v[222:223], v[76:77], v[168:169], v[222:223]
	v_pk_fma_f32 v[128:129], v[22:23], v[170:171], v[128:129]
	v_pk_fma_f32 v[134:135], v[38:39], v[170:171], v[134:135]
	v_pk_fma_f32 v[220:221], v[54:55], v[170:171], v[220:221]
	v_pk_fma_f32 v[222:223], v[70:71], v[170:171], v[222:223]
	v_pk_fma_f32 v[128:129], v[24:25], v[172:173], v[128:129]
	v_pk_fma_f32 v[134:135], v[40:41], v[172:173], v[134:135]
	v_pk_fma_f32 v[220:221], v[56:57], v[172:173], v[220:221]
	v_pk_fma_f32 v[222:223], v[72:73], v[172:173], v[222:223]
	v_pk_fma_f32 v[128:129], v[18:19], v[174:175], v[128:129]
	v_pk_fma_f32 v[134:135], v[34:35], v[174:175], v[134:135]
	v_pk_fma_f32 v[220:221], v[50:51], v[174:175], v[220:221]
	v_pk_fma_f32 v[222:223], v[66:67], v[174:175], v[222:223]
	v_pk_fma_f32 v[128:129], v[20:21], v[176:177], v[128:129]
	v_pk_fma_f32 v[134:135], v[36:37], v[176:177], v[134:135]
	v_pk_fma_f32 v[220:221], v[52:53], v[176:177], v[220:221]
	v_pk_fma_f32 v[222:223], v[68:69], v[176:177], v[222:223]
	v_add_f32_e32 v128, v128, v129
	v_add_f32_e32 v134, v134, v135
	v_add_f32_e32 v220, v220, v221
	v_add_f32_e32 v222, v222, v223
	v_add_f32_dpp v128, v128, v128 quad_perm:[1,0,3,2] row_mask:0xf bank_mask:0xf bound_ctrl:1
	v_add_f32_dpp v134, v134, v134 quad_perm:[1,0,3,2] row_mask:0xf bank_mask:0xf bound_ctrl:1
	v_add_f32_dpp v220, v220, v220 quad_perm:[1,0,3,2] row_mask:0xf bank_mask:0xf bound_ctrl:1
	v_add_f32_dpp v222, v222, v222 quad_perm:[1,0,3,2] row_mask:0xf bank_mask:0xf bound_ctrl:1
	v_add_f32_dpp v128, v128, v128 quad_perm:[2,3,0,1] row_mask:0xf bank_mask:0xf bound_ctrl:1
	v_add_f32_dpp v134, v134, v134 quad_perm:[2,3,0,1] row_mask:0xf bank_mask:0xf bound_ctrl:1
	v_add_f32_dpp v220, v220, v220 quad_perm:[2,3,0,1] row_mask:0xf bank_mask:0xf bound_ctrl:1
	v_add_f32_dpp v222, v222, v222 quad_perm:[2,3,0,1] row_mask:0xf bank_mask:0xf bound_ctrl:1
	v_add_f32_dpp v128, v128, v128 row_half_mirror row_mask:0xf bank_mask:0xf bound_ctrl:1
	v_add_f32_dpp v134, v134, v134 row_half_mirror row_mask:0xf bank_mask:0xf bound_ctrl:1
	v_add_f32_dpp v220, v220, v220 row_half_mirror row_mask:0xf bank_mask:0xf bound_ctrl:1
	v_add_f32_dpp v222, v222, v222 row_half_mirror row_mask:0xf bank_mask:0xf bound_ctrl:1
	v_mul_f32_e32 v128, v128, v236
	v_mul_f32_e32 v134, v134, v236
	v_mul_f32_e32 v220, v220, v236
	v_mul_f32_e32 v222, v222, v236
	s_and_saveexec_b64 s[68:69], s[8:9]
	v_cndmask_b32_e64 v226, 0, v128, s[10:11]
	v_cndmask_b32_e64 v226, v226, v134, s[12:13]
	v_cndmask_b32_e64 v226, v226, v220, s[14:15]
	v_cndmask_b32_e64 v226, v226, v222, s[16:17]
	v_add_co_u32_e32 v228, vcc, 0xdc04000, v224
	v_cvt_pk_bf16_f32 v226, v226, s0
	s_nop 0
	v_addc_co_u32_e32 v229, vcc, 0, v225, vcc
	global_store_short v[228:229], v226, off offset:3072
	s_or_b64 exec, exec, s[68:69]
	s_add_i32 s73, s73, 8
	s_add_u32 s66, s66, 0x6800
	s_addc_u32 s67, s67, 0
	v_add_u32_e32 v91, 0x100, v91
	s_cmp_eq_u32 s66, 0x1a000
	v_add_u32_e32 v84, 0x400, v84
	s_cbranch_scc0 .Lc2_fast
	v_pk_mul_f32 v[30:31], v[30:31], v[236:237] op_sel_hi:[1,0]
	v_pk_mul_f32 v[32:33], v[32:33], v[236:237] op_sel_hi:[1,0]
	v_pk_mul_f32 v[26:27], v[26:27], v[236:237] op_sel_hi:[1,0]
	v_pk_mul_f32 v[28:29], v[28:29], v[236:237] op_sel_hi:[1,0]
	v_pk_mul_f32 v[22:23], v[22:23], v[236:237] op_sel_hi:[1,0]
	v_pk_mul_f32 v[24:25], v[24:25], v[236:237] op_sel_hi:[1,0]
	v_pk_mul_f32 v[18:19], v[18:19], v[236:237] op_sel_hi:[1,0]
	v_pk_mul_f32 v[20:21], v[20:21], v[236:237] op_sel_hi:[1,0]
	v_pk_mul_f32 v[46:47], v[46:47], v[236:237] op_sel_hi:[1,0]
	v_pk_mul_f32 v[48:49], v[48:49], v[236:237] op_sel_hi:[1,0]
	v_pk_mul_f32 v[42:43], v[42:43], v[236:237] op_sel_hi:[1,0]
	v_pk_mul_f32 v[44:45], v[44:45], v[236:237] op_sel_hi:[1,0]
	v_pk_mul_f32 v[38:39], v[38:39], v[236:237] op_sel_hi:[1,0]
	v_pk_mul_f32 v[40:41], v[40:41], v[236:237] op_sel_hi:[1,0]
	v_pk_mul_f32 v[34:35], v[34:35], v[236:237] op_sel_hi:[1,0]
	v_pk_mul_f32 v[36:37], v[36:37], v[236:237] op_sel_hi:[1,0]
	v_pk_mul_f32 v[62:63], v[62:63], v[236:237] op_sel_hi:[1,0]
	v_pk_mul_f32 v[64:65], v[64:65], v[236:237] op_sel_hi:[1,0]
	v_pk_mul_f32 v[58:59], v[58:59], v[236:237] op_sel_hi:[1,0]
	v_pk_mul_f32 v[60:61], v[60:61], v[236:237] op_sel_hi:[1,0]
	v_pk_mul_f32 v[54:55], v[54:55], v[236:237] op_sel_hi:[1,0]
	v_pk_mul_f32 v[56:57], v[56:57], v[236:237] op_sel_hi:[1,0]
	v_pk_mul_f32 v[50:51], v[50:51], v[236:237] op_sel_hi:[1,0]
	v_pk_mul_f32 v[52:53], v[52:53], v[236:237] op_sel_hi:[1,0]
	v_pk_mul_f32 v[78:79], v[78:79], v[236:237] op_sel_hi:[1,0]
	v_pk_mul_f32 v[80:81], v[80:81], v[236:237] op_sel_hi:[1,0]
	v_pk_mul_f32 v[74:75], v[74:75], v[236:237] op_sel_hi:[1,0]
	v_pk_mul_f32 v[76:77], v[76:77], v[236:237] op_sel_hi:[1,0]
	v_pk_mul_f32 v[70:71], v[70:71], v[236:237] op_sel_hi:[1,0]
	v_pk_mul_f32 v[72:73], v[72:73], v[236:237] op_sel_hi:[1,0]
	v_pk_mul_f32 v[66:67], v[66:67], v[236:237] op_sel_hi:[1,0]
	v_pk_mul_f32 v[68:69], v[68:69], v[236:237] op_sel_hi:[1,0]
	s_branch .LBB0_660
